# v48 + norm loops prefetch the next row pair's loads before the stores (norm_gen2)
# baseline (speedup 1.0000x reference)
; DI void norm_phase(const float* lat, const float* ctxp, int nrows, const float* g, const float* modl, int shift_off, int scale_off,
;                    bf16_t* H, int bid, int nb) {
;     ...
;   for (int r8 = bid; r8 < nrows / 8; r8 += nb) {
;     f32x4 v[2][4]; float ss[2] = {0.f, 0.f};
; #pragma unroll
;     for (int h = 0; h < 2; ++h) {
;       const int row = r8 * 8 + wave + 4 * h;
;       const float* src = row < TL ? lat + (size_t)row * DM : ctxp + (size_t)(row - TL) * DM;
; #pragma unroll
;       for (int i = 0; i < 4; ++i) v[h][i] = *(const f32x4*)(src + lane * 4 + 256 * i);
;     }
; #pragma unroll
;     for (int h = 0; h < 2; ++h) {
; #pragma unroll
;       for (int i = 0; i < 4; ++i) ss[h] += v[h][i][0] * v[h][i][0] + v[h][i][1] * v[h][i][1] + v[h][i][2] * v[h][i][2] + v[h][i][3] * v[h][i][3];
;       ss[h] = wave_sum(ss[h]);
;     }
; #pragma unroll
;     for (int h = 0; h < 2; ++h) {
;       const int row = r8 * 8 + wave + 4 * h;
;       const int mi = row < TL ? (row >> 14) : 2;
;       const float* sh = modl + mi * 6144 + shift_off;
;       const float* sc = modl + mi * 6144 + scale_off;
;       const float rs = rsqrtf(ss[h] * (1.f / 1024.f) + EPS);
.LBB0_67:
	s_or_b64 exec, exec, s[2:3]
	v_lshl_add_u64 v[0:1], v[0:1], 0, v[38:39]
	global_load_dwordx4 v[16:19], v[0:1], off
	global_load_dwordx4 v[8:11], v[0:1], off offset:1024
	global_load_dwordx4 v[4:7], v[0:1], off offset:2048
	s_nop 0
	global_load_dwordx4 v[0:3], v[0:1], off offset:3072
	s_mov_b32 s46, 0x4000
	s_mov_b32 s47, 0
	s_waitcnt vmcnt(0)
.Lnorm_loop1:
	v_min_i32_e32 v168, 0x8000, v36
	v_readlane_b32 s24, v254, 46
	v_ashrrev_i32_e32 v168, 14, v168
	v_readlane_b32 s25, v254, 47
	v_mul_i32_i24_e32 v168, 0x1800, v168
	v_lshlrev_b64 v[182:183], 11, v[36:37]
	v_ashrrev_i32_e32 v169, 31, v168
	v_lshlrev_b64 v[98:99], 11, v[46:47]
	v_lshl_add_u64 v[170:171], v[168:169], 2, s[24:25]
	v_lshl_add_u64 v[172:173], v[170:171], 0, s[66:67]
	v_lshl_add_u64 v[170:171], v[170:171], 0, v[38:39]
	v_lshl_add_u64 v[172:173], v[172:173], 0, v[38:39]
	global_load_dwordx4 v[100:103], v[32:33], off
	global_load_dwordx4 v[116:119], v[172:173], off
	global_load_dwordx4 v[132:135], v[170:171], off
	global_load_dwordx4 v[104:107], v[32:33], off offset:1024
	global_load_dwordx4 v[120:123], v[172:173], off offset:1024
	global_load_dwordx4 v[136:139], v[170:171], off offset:1024
	global_load_dwordx4 v[108:111], v[32:33], off offset:2048
	global_load_dwordx4 v[124:127], v[172:173], off offset:2048
	global_load_dwordx4 v[140:143], v[170:171], off offset:2048
	global_load_dwordx4 v[112:115], v[32:33], off offset:3072
	global_load_dwordx4 v[128:131], v[172:173], off offset:3072
	global_load_dwordx4 v[164:167], v[170:171], off offset:3072
	v_lshl_add_u64 v[182:183], v[34:35], 0, v[182:183]
	v_lshl_add_u64 v[98:99], v[34:35], 0, v[98:99]
	v_readlane_b32 s2, v252, 2
	s_add_i32 s21, s21, s2
	s_cmpk_lt_i32 s21, 0x1040
	s_cselect_b32 s45, 1, 0
	v_readlane_b32 s2, v253, 43
	s_nop 0
	s_cselect_b32 s44, s2, 0
	v_add_u32_e32 v232, s44, v36
	v_cmp_gt_i32_e32 vcc, s34, v232
	v_add_u32_e32 v238, 0xffff8000, v232
	v_ashrrev_i32_e32 v239, 31, v232
	v_cndmask_b32_e32 v199, v54, v55, vcc
	v_cndmask_b32_e32 v198, v56, v57, vcc
	v_cndmask_b32_e32 v239, 0, v239, vcc
	v_cndmask_b32_e32 v238, v238, v232, vcc
	v_lshlrev_b64 v[238:239], 12, v[238:239]
	v_lshl_add_u64 v[198:199], v[198:199], 0, v[238:239]
	v_lshl_add_u64 v[198:199], v[198:199], 0, v[38:39]
	global_load_dwordx4 v[184:187], v[198:199], off
	global_load_dwordx4 v[188:191], v[198:199], off offset:1024
	global_load_dwordx4 v[200:203], v[198:199], off offset:2048
	global_load_dwordx4 v[204:207], v[198:199], off offset:3072
	v_lshl_add_u64 v[198:199], v[198:199], 0, s[46:47]
	global_load_dwordx4 v[208:211], v[198:199], off
	global_load_dwordx4 v[240:243], v[198:199], off offset:1024
	global_load_dwordx4 v[244:247], v[198:199], off offset:2048
	global_load_dwordx4 v[248:251], v[198:199], off offset:3072
	s_waitcnt vmcnt(8)
	v_mul_f32_e32 v174, v28, v28
	v_fmac_f32_e32 v174, v29, v29
	v_fmac_f32_e32 v174, v30, v30
	v_fmac_f32_e32 v174, v31, v31
	v_fmac_f32_e32 v174, v24, v24
	v_fmac_f32_e32 v174, v25, v25
	v_fmac_f32_e32 v174, v26, v26
	v_fmac_f32_e32 v174, v27, v27
	v_fmac_f32_e32 v174, v20, v20
	v_fmac_f32_e32 v174, v21, v21
	v_fmac_f32_e32 v174, v22, v22
	v_fmac_f32_e32 v174, v23, v23
	v_fmac_f32_e32 v174, v12, v12
	v_fmac_f32_e32 v174, v13, v13
	v_fmac_f32_e32 v174, v14, v14
	v_fmac_f32_e32 v174, v15, v15
	v_mul_f32_e32 v175, v16, v16
	v_fmac_f32_e32 v175, v17, v17
	v_fmac_f32_e32 v175, v18, v18
	v_fmac_f32_e32 v175, v19, v19
	v_fmac_f32_e32 v175, v8, v8
	v_fmac_f32_e32 v175, v9, v9
	v_fmac_f32_e32 v175, v10, v10
	v_fmac_f32_e32 v175, v11, v11
	v_fmac_f32_e32 v175, v4, v4
	v_fmac_f32_e32 v175, v5, v5
	v_fmac_f32_e32 v175, v6, v6
	v_fmac_f32_e32 v175, v7, v7
	v_fmac_f32_e32 v175, v0, v0
	v_fmac_f32_e32 v175, v1, v1
	v_fmac_f32_e32 v175, v2, v2
	v_fmac_f32_e32 v175, v3, v3
	ds_bpermute_b32 v176, v48, v174
	ds_bpermute_b32 v177, v48, v175
	s_waitcnt lgkmcnt(0)
	v_add_f32_e32 v174, v174, v176
	v_add_f32_e32 v175, v175, v177
	ds_bpermute_b32 v176, v49, v174
	ds_bpermute_b32 v177, v49, v175
	s_waitcnt lgkmcnt(0)
	v_add_f32_e32 v174, v174, v176
	v_add_f32_e32 v175, v175, v177
	ds_bpermute_b32 v176, v50, v174
	ds_bpermute_b32 v177, v50, v175
	s_waitcnt lgkmcnt(0)
	v_add_f32_e32 v174, v174, v176
	v_add_f32_e32 v175, v175, v177
	ds_bpermute_b32 v176, v51, v174
	ds_bpermute_b32 v177, v51, v175
	s_waitcnt lgkmcnt(0)
	v_add_f32_e32 v174, v174, v176
	v_add_f32_e32 v175, v175, v177
	ds_bpermute_b32 v176, v52, v174
	ds_bpermute_b32 v177, v52, v175
	s_waitcnt lgkmcnt(0)
	v_add_f32_e32 v174, v174, v176
	v_add_f32_e32 v175, v175, v177
	ds_bpermute_b32 v176, v53, v174
	ds_bpermute_b32 v177, v53, v175
	s_waitcnt lgkmcnt(0)
; DI unsigned pk2(float a, float b) { f32x2 v = {a, b}; return __builtin_bit_cast(unsigned, __builtin_convertvector(v, bf16x2_t)); }
; DI void norm_phase(const float* lat, const float* ctxp, int nrows, const float* g, const float* modl, int shift_off, int scale_off,
;                    bf16_t* H, int bid, int nb) {
;     ...
;     for (int h = 0; h < 2; ++h) {
;       const int row = r8 * 8 + wave + 4 * h;
;       const int mi = row < TL ? (row >> 14) : 2;
;       const float* sh = modl + mi * 6144 + shift_off;
;       const float* sc = modl + mi * 6144 + scale_off;
;       const float rs = rsqrtf(ss[h] * (1.f / 1024.f) + EPS);
; #pragma unroll
;       for (int i = 0; i < 4; ++i) {
;         const int col = lane * 4 + 256 * i;
;         const f32x4 gg = *(const f32x4*)(g + col), s4 = *(const f32x4*)(sc + col), h4 = *(const f32x4*)(sh + col);
;         float y[4];
; #pragma unroll
;         for (int j = 0; j < 4; ++j) y[j] = (v[h][i][j] * rs * gg[j]) * (1.f + s4[j]) + h4[j];
;         u32x2 w; w[0] = pk2(y[0], y[1]); w[1] = pk2(y[2], y[3]);
;         *(u32x2*)(H + (size_t)row * DM + col) = w;
;       }
;     }
;   }
	v_add_f32_e32 v174, v174, v176
	v_add_f32_e32 v175, v175, v177
	s_mov_b32 s2, 0x3a800000
	v_fma_f32 v174, v174, s2, v194
	v_fma_f32 v175, v175, s2, v194
	v_rsq_f32_e32 v178, v174
	v_rsq_f32_e32 v180, v175
	v_pk_add_f32 v[116:117], v[116:117], 1.0 op_sel_hi:[1,0]
	v_pk_add_f32 v[118:119], v[118:119], 1.0 op_sel_hi:[1,0]
	v_pk_mul_f32 v[28:29], v[28:29], v[178:179] op_sel_hi:[1,0]
	v_pk_mul_f32 v[30:31], v[30:31], v[178:179] op_sel_hi:[1,0]
	v_pk_mul_f32 v[28:29], v[100:101], v[28:29]
	v_pk_mul_f32 v[30:31], v[102:103], v[30:31]
	v_pk_fma_f32 v[28:29], v[116:117], v[28:29], v[132:133]
	v_pk_fma_f32 v[30:31], v[118:119], v[30:31], v[134:135]
	v_cvt_pk_bf16_f32 v28, v28, v29
	v_cvt_pk_bf16_f32 v29, v30, v31
	global_store_dwordx2 v[182:183], v[28:29], off
	v_pk_mul_f32 v[16:17], v[16:17], v[180:181] op_sel_hi:[1,0]
	v_pk_mul_f32 v[18:19], v[18:19], v[180:181] op_sel_hi:[1,0]
	v_pk_mul_f32 v[16:17], v[100:101], v[16:17]
	v_pk_mul_f32 v[18:19], v[102:103], v[18:19]
	v_pk_fma_f32 v[16:17], v[116:117], v[16:17], v[132:133]
	v_pk_fma_f32 v[18:19], v[118:119], v[18:19], v[134:135]
	v_cvt_pk_bf16_f32 v16, v16, v17
	v_cvt_pk_bf16_f32 v17, v18, v19
	global_store_dwordx2 v[98:99], v[16:17], off
	v_pk_add_f32 v[120:121], v[120:121], 1.0 op_sel_hi:[1,0]
	v_pk_add_f32 v[122:123], v[122:123], 1.0 op_sel_hi:[1,0]
	v_pk_mul_f32 v[24:25], v[24:25], v[178:179] op_sel_hi:[1,0]
	v_pk_mul_f32 v[26:27], v[26:27], v[178:179] op_sel_hi:[1,0]
	v_pk_mul_f32 v[24:25], v[104:105], v[24:25]
	v_pk_mul_f32 v[26:27], v[106:107], v[26:27]
	v_pk_fma_f32 v[24:25], v[120:121], v[24:25], v[136:137]
	v_pk_fma_f32 v[26:27], v[122:123], v[26:27], v[138:139]
	v_cvt_pk_bf16_f32 v24, v24, v25
	v_cvt_pk_bf16_f32 v25, v26, v27
	global_store_dwordx2 v[182:183], v[24:25], off offset:512
	v_pk_mul_f32 v[8:9], v[8:9], v[180:181] op_sel_hi:[1,0]
	v_pk_mul_f32 v[10:11], v[10:11], v[180:181] op_sel_hi:[1,0]
	v_pk_mul_f32 v[8:9], v[104:105], v[8:9]
	v_pk_mul_f32 v[10:11], v[106:107], v[10:11]
	v_pk_fma_f32 v[8:9], v[120:121], v[8:9], v[136:137]
	v_pk_fma_f32 v[10:11], v[122:123], v[10:11], v[138:139]
	v_cvt_pk_bf16_f32 v8, v8, v9
	v_cvt_pk_bf16_f32 v9, v10, v11
	global_store_dwordx2 v[98:99], v[8:9], off offset:512
	v_pk_add_f32 v[124:125], v[124:125], 1.0 op_sel_hi:[1,0]
	v_pk_add_f32 v[126:127], v[126:127], 1.0 op_sel_hi:[1,0]
	v_pk_mul_f32 v[20:21], v[20:21], v[178:179] op_sel_hi:[1,0]
	v_pk_mul_f32 v[22:23], v[22:23], v[178:179] op_sel_hi:[1,0]
	v_pk_mul_f32 v[20:21], v[108:109], v[20:21]
	v_pk_mul_f32 v[22:23], v[110:111], v[22:23]
	v_pk_fma_f32 v[20:21], v[124:125], v[20:21], v[140:141]
	v_pk_fma_f32 v[22:23], v[126:127], v[22:23], v[142:143]
	v_cvt_pk_bf16_f32 v20, v20, v21
	v_cvt_pk_bf16_f32 v21, v22, v23
	global_store_dwordx2 v[182:183], v[20:21], off offset:1024
	v_pk_mul_f32 v[4:5], v[4:5], v[180:181] op_sel_hi:[1,0]
	v_pk_mul_f32 v[6:7], v[6:7], v[180:181] op_sel_hi:[1,0]
	v_pk_mul_f32 v[4:5], v[108:109], v[4:5]
	v_pk_mul_f32 v[6:7], v[110:111], v[6:7]
	v_pk_fma_f32 v[4:5], v[124:125], v[4:5], v[140:141]
	v_pk_fma_f32 v[6:7], v[126:127], v[6:7], v[142:143]
	v_cvt_pk_bf16_f32 v4, v4, v5
	v_cvt_pk_bf16_f32 v5, v6, v7
	global_store_dwordx2 v[98:99], v[4:5], off offset:1024
	v_pk_add_f32 v[128:129], v[128:129], 1.0 op_sel_hi:[1,0]
	v_pk_add_f32 v[130:131], v[130:131], 1.0 op_sel_hi:[1,0]
	v_pk_mul_f32 v[12:13], v[12:13], v[178:179] op_sel_hi:[1,0]
	v_pk_mul_f32 v[14:15], v[14:15], v[178:179] op_sel_hi:[1,0]
	v_pk_mul_f32 v[12:13], v[112:113], v[12:13]
	v_pk_mul_f32 v[14:15], v[114:115], v[14:15]
	v_pk_fma_f32 v[12:13], v[128:129], v[12:13], v[164:165]
	v_pk_fma_f32 v[14:15], v[130:131], v[14:15], v[166:167]
	v_cvt_pk_bf16_f32 v12, v12, v13
	v_cvt_pk_bf16_f32 v13, v14, v15
	global_store_dwordx2 v[182:183], v[12:13], off offset:1536
	v_pk_mul_f32 v[0:1], v[0:1], v[180:181] op_sel_hi:[1,0]
	v_pk_mul_f32 v[2:3], v[2:3], v[180:181] op_sel_hi:[1,0]
	v_pk_mul_f32 v[0:1], v[112:113], v[0:1]
	v_pk_mul_f32 v[2:3], v[114:115], v[2:3]
	v_pk_fma_f32 v[0:1], v[128:129], v[0:1], v[164:165]
	v_pk_fma_f32 v[2:3], v[130:131], v[2:3], v[166:167]
	v_cvt_pk_bf16_f32 v0, v0, v1
	v_cvt_pk_bf16_f32 v1, v2, v3
	global_store_dwordx2 v[98:99], v[0:1], off offset:1536
	s_waitcnt vmcnt(8)
	v_mov_b32_e32 v28, v184
	v_mov_b32_e32 v29, v185
	v_mov_b32_e32 v30, v186
	v_mov_b32_e32 v31, v187
	v_mov_b32_e32 v24, v188
	v_mov_b32_e32 v25, v189
	v_mov_b32_e32 v26, v190
	v_mov_b32_e32 v27, v191
	v_mov_b32_e32 v20, v200
	v_mov_b32_e32 v21, v201
	v_mov_b32_e32 v22, v202
	v_mov_b32_e32 v23, v203
	v_mov_b32_e32 v12, v204
	v_mov_b32_e32 v13, v205
	v_mov_b32_e32 v14, v206
	v_mov_b32_e32 v15, v207
	v_mov_b32_e32 v16, v208
	v_mov_b32_e32 v17, v209
	v_mov_b32_e32 v18, v210
	v_mov_b32_e32 v19, v211
	v_mov_b32_e32 v8, v240
	v_mov_b32_e32 v9, v241
	v_mov_b32_e32 v10, v242
	v_mov_b32_e32 v11, v243
	v_mov_b32_e32 v4, v244
	v_mov_b32_e32 v5, v245
	v_mov_b32_e32 v6, v246
	v_mov_b32_e32 v7, v247
	v_mov_b32_e32 v0, v248
	v_mov_b32_e32 v1, v249
	v_mov_b32_e32 v2, v250
	v_mov_b32_e32 v3, v251
	v_mov_b32_e32 v36, v232
	v_ashrrev_i32_e32 v37, 31, v232
	v_add_u32_e32 v46, 4, v232
	s_cmp_lg_u32 s45, 0
	v_ashrrev_i32_e32 v47, 31, v46
	s_cbranch_scc1 .Lnorm_loop1
	s_branch .LBB0_72

; DI void norm_phase(const float* lat, const float* ctxp, int nrows, const float* g, const float* modl, int shift_off, int scale_off,
;                    bf16_t* H, int bid, int nb) {
;     ...
;   for (int r8 = bid; r8 < nrows / 8; r8 += nb) {
;     f32x4 v[2][4]; float ss[2] = {0.f, 0.f};
; #pragma unroll
;     for (int h = 0; h < 2; ++h) {
;       const int row = r8 * 8 + wave + 4 * h;
;       const float* src = row < TL ? lat + (size_t)row * DM : ctxp + (size_t)(row - TL) * DM;
; #pragma unroll
;       for (int i = 0; i < 4; ++i) v[h][i] = *(const f32x4*)(src + lane * 4 + 256 * i);
;     }
; #pragma unroll
;     for (int h = 0; h < 2; ++h) {
; #pragma unroll
;       for (int i = 0; i < 4; ++i) ss[h] += v[h][i][0] * v[h][i][0] + v[h][i][1] * v[h][i][1] + v[h][i][2] * v[h][i][2] + v[h][i][3] * v[h][i][3];
;       ss[h] = wave_sum(ss[h]);
;     }
; #pragma unroll
;     for (int h = 0; h < 2; ++h) {
;       const int row = r8 * 8 + wave + 4 * h;
;       const int mi = row < TL ? (row >> 14) : 2;
;       const float* sh = modl + mi * 6144 + shift_off;
;       const float* sc = modl + mi * 6144 + scale_off;
;       const float rs = rsqrtf(ss[h] * (1.f / 1024.f) + EPS);
.LBB0_640:
	s_or_b64 exec, exec, s[2:3]
	v_lshl_add_u64 v[0:1], v[0:1], 0, v[192:193]
	global_load_dwordx4 v[16:19], v[0:1], off
	global_load_dwordx4 v[8:11], v[0:1], off offset:1024
	global_load_dwordx4 v[4:7], v[0:1], off offset:2048
	s_nop 0
	global_load_dwordx4 v[0:3], v[0:1], off offset:3072
	s_mov_b32 s46, 0x4000
	s_mov_b32 s47, 0
	s_waitcnt vmcnt(0)
.Lnorm_loop2:
	v_min_i32_e32 v168, 0x8000, v38
	v_readlane_b32 s28, v254, 46
	v_ashrrev_i32_e32 v168, 14, v168
	v_readlane_b32 s29, v254, 47
	v_mul_i32_i24_e32 v168, 0x1800, v168
	v_lshlrev_b64 v[182:183], 11, v[38:39]
	v_ashrrev_i32_e32 v169, 31, v168
	v_lshlrev_b64 v[98:99], 11, v[46:47]
	v_lshl_add_u64 v[170:171], v[168:169], 2, s[28:29]
	s_mov_b64 s[24:25], 0x3000
	s_mov_b64 s[26:27], 0x4000
	v_lshl_add_u64 v[172:173], v[170:171], 0, s[26:27]
	v_lshl_add_u64 v[170:171], v[170:171], 0, s[24:25]
	v_lshl_add_u64 v[170:171], v[170:171], 0, v[192:193]
	v_lshl_add_u64 v[172:173], v[172:173], 0, v[192:193]
	global_load_dwordx4 v[100:103], v[34:35], off
	global_load_dwordx4 v[116:119], v[172:173], off
	global_load_dwordx4 v[132:135], v[170:171], off
	global_load_dwordx4 v[104:107], v[34:35], off offset:1024
	global_load_dwordx4 v[120:123], v[172:173], off offset:1024
	global_load_dwordx4 v[136:139], v[170:171], off offset:1024
	global_load_dwordx4 v[108:111], v[34:35], off offset:2048
	global_load_dwordx4 v[124:127], v[172:173], off offset:2048
	global_load_dwordx4 v[140:143], v[170:171], off offset:2048
	global_load_dwordx4 v[112:115], v[34:35], off offset:3072
	global_load_dwordx4 v[128:131], v[172:173], off offset:3072
	global_load_dwordx4 v[164:167], v[170:171], off offset:3072
	v_lshl_add_u64 v[182:183], v[36:37], 0, v[182:183]
	v_lshl_add_u64 v[98:99], v[36:37], 0, v[98:99]
	v_readlane_b32 s2, v252, 2
	s_add_i32 s22, s22, s2
	s_cmp_lt_i32 s22, s21
	s_cselect_b32 s45, 1, 0
	v_readlane_b32 s2, v253, 43
	s_nop 0
	s_cselect_b32 s44, s2, 0
	v_add_u32_e32 v232, s44, v38
	v_cmp_gt_i32_e32 vcc, s34, v232
	v_add_u32_e32 v238, 0xffff8000, v232
	v_ashrrev_i32_e32 v239, 31, v232
	v_mov_b32_e32 v199, s7
	v_mov_b32_e32 v197, s5
	v_cndmask_b32_e32 v199, v199, v197, vcc
	v_mov_b32_e32 v198, s6
	v_mov_b32_e32 v197, s4
	v_cndmask_b32_e32 v198, v198, v197, vcc
	v_cndmask_b32_e32 v239, 0, v239, vcc
	v_cndmask_b32_e32 v238, v238, v232, vcc
	v_lshlrev_b64 v[238:239], 12, v[238:239]
	v_lshl_add_u64 v[198:199], v[198:199], 0, v[238:239]
	v_lshl_add_u64 v[198:199], v[198:199], 0, v[192:193]
	global_load_dwordx4 v[184:187], v[198:199], off
	global_load_dwordx4 v[188:191], v[198:199], off offset:1024
	global_load_dwordx4 v[200:203], v[198:199], off offset:2048
	global_load_dwordx4 v[204:207], v[198:199], off offset:3072
	v_lshl_add_u64 v[198:199], v[198:199], 0, s[46:47]
	global_load_dwordx4 v[208:211], v[198:199], off
	global_load_dwordx4 v[240:243], v[198:199], off offset:1024
	global_load_dwordx4 v[244:247], v[198:199], off offset:2048
	global_load_dwordx4 v[248:251], v[198:199], off offset:3072
	s_waitcnt vmcnt(8)
	v_mul_f32_e32 v174, v28, v28
	v_fmac_f32_e32 v174, v29, v29
	v_fmac_f32_e32 v174, v30, v30
	v_fmac_f32_e32 v174, v31, v31
	v_fmac_f32_e32 v174, v24, v24
	v_fmac_f32_e32 v174, v25, v25
	v_fmac_f32_e32 v174, v26, v26
	v_fmac_f32_e32 v174, v27, v27
	v_fmac_f32_e32 v174, v20, v20
	v_fmac_f32_e32 v174, v21, v21
	v_fmac_f32_e32 v174, v22, v22
	v_fmac_f32_e32 v174, v23, v23
	v_fmac_f32_e32 v174, v12, v12
	v_fmac_f32_e32 v174, v13, v13
	v_fmac_f32_e32 v174, v14, v14
	v_fmac_f32_e32 v174, v15, v15
	v_mul_f32_e32 v175, v16, v16
	v_fmac_f32_e32 v175, v17, v17
	v_fmac_f32_e32 v175, v18, v18
	v_fmac_f32_e32 v175, v19, v19
	v_fmac_f32_e32 v175, v8, v8
	v_fmac_f32_e32 v175, v9, v9
	v_fmac_f32_e32 v175, v10, v10
	v_fmac_f32_e32 v175, v11, v11
	v_fmac_f32_e32 v175, v4, v4
	v_fmac_f32_e32 v175, v5, v5
	v_fmac_f32_e32 v175, v6, v6
	v_fmac_f32_e32 v175, v7, v7
	v_fmac_f32_e32 v175, v0, v0
	v_fmac_f32_e32 v175, v1, v1
	v_fmac_f32_e32 v175, v2, v2
	v_fmac_f32_e32 v175, v3, v3
	ds_bpermute_b32 v176, v33, v174
	ds_bpermute_b32 v177, v33, v175
	s_waitcnt lgkmcnt(0)
	v_add_f32_e32 v174, v174, v176
	v_add_f32_e32 v175, v175, v177
	ds_bpermute_b32 v176, v48, v174
	ds_bpermute_b32 v177, v48, v175
	s_waitcnt lgkmcnt(0)
	v_add_f32_e32 v174, v174, v176
	v_add_f32_e32 v175, v175, v177
	ds_bpermute_b32 v176, v49, v174
	ds_bpermute_b32 v177, v49, v175
	s_waitcnt lgkmcnt(0)
	v_add_f32_e32 v174, v174, v176
	v_add_f32_e32 v175, v175, v177
	ds_bpermute_b32 v176, v50, v174
	ds_bpermute_b32 v177, v50, v175
	s_waitcnt lgkmcnt(0)
	v_add_f32_e32 v174, v174, v176
	v_add_f32_e32 v175, v175, v177
	ds_bpermute_b32 v176, v51, v174
	ds_bpermute_b32 v177, v51, v175
	s_waitcnt lgkmcnt(0)
	v_add_f32_e32 v174, v174, v176
	v_add_f32_e32 v175, v175, v177
	ds_bpermute_b32 v176, v52, v174
	ds_bpermute_b32 v177, v52, v175
	s_waitcnt lgkmcnt(0)
; DI unsigned pk2(float a, float b) { f32x2 v = {a, b}; return __builtin_bit_cast(unsigned, __builtin_convertvector(v, bf16x2_t)); }
; DI void norm_phase(const float* lat, const float* ctxp, int nrows, const float* g, const float* modl, int shift_off, int scale_off,
;                    bf16_t* H, int bid, int nb) {
;     ...
;     for (int h = 0; h < 2; ++h) {
;       const int row = r8 * 8 + wave + 4 * h;
;       const int mi = row < TL ? (row >> 14) : 2;
;       const float* sh = modl + mi * 6144 + shift_off;
;       const float* sc = modl + mi * 6144 + scale_off;
;       const float rs = rsqrtf(ss[h] * (1.f / 1024.f) + EPS);
; #pragma unroll
;       for (int i = 0; i < 4; ++i) {
;         const int col = lane * 4 + 256 * i;
;         const f32x4 gg = *(const f32x4*)(g + col), s4 = *(const f32x4*)(sc + col), h4 = *(const f32x4*)(sh + col);
;         float y[4];
; #pragma unroll
;         for (int j = 0; j < 4; ++j) y[j] = (v[h][i][j] * rs * gg[j]) * (1.f + s4[j]) + h4[j];
;         u32x2 w; w[0] = pk2(y[0], y[1]); w[1] = pk2(y[2], y[3]);
;         *(u32x2*)(H + (size_t)row * DM + col) = w;
;       }
;     }
;   }
	v_add_f32_e32 v174, v174, v176
	v_add_f32_e32 v175, v175, v177
	s_mov_b32 s2, 0x3a800000
	v_fma_f32 v174, v174, s2, v194
	v_fma_f32 v175, v175, s2, v194
	v_rsq_f32_e32 v178, v174
	v_rsq_f32_e32 v180, v175
	v_pk_add_f32 v[116:117], v[116:117], 1.0 op_sel_hi:[1,0]
	v_pk_add_f32 v[118:119], v[118:119], 1.0 op_sel_hi:[1,0]
	v_pk_mul_f32 v[28:29], v[28:29], v[178:179] op_sel_hi:[1,0]
	v_pk_mul_f32 v[30:31], v[30:31], v[178:179] op_sel_hi:[1,0]
	v_pk_mul_f32 v[28:29], v[100:101], v[28:29]
	v_pk_mul_f32 v[30:31], v[102:103], v[30:31]
	v_pk_fma_f32 v[28:29], v[116:117], v[28:29], v[132:133]
	v_pk_fma_f32 v[30:31], v[118:119], v[30:31], v[134:135]
	v_cvt_pk_bf16_f32 v28, v28, v29
	v_cvt_pk_bf16_f32 v29, v30, v31
	global_store_dwordx2 v[182:183], v[28:29], off
	v_pk_mul_f32 v[16:17], v[16:17], v[180:181] op_sel_hi:[1,0]
	v_pk_mul_f32 v[18:19], v[18:19], v[180:181] op_sel_hi:[1,0]
	v_pk_mul_f32 v[16:17], v[100:101], v[16:17]
	v_pk_mul_f32 v[18:19], v[102:103], v[18:19]
	v_pk_fma_f32 v[16:17], v[116:117], v[16:17], v[132:133]
	v_pk_fma_f32 v[18:19], v[118:119], v[18:19], v[134:135]
	v_cvt_pk_bf16_f32 v16, v16, v17
	v_cvt_pk_bf16_f32 v17, v18, v19
	global_store_dwordx2 v[98:99], v[16:17], off
	v_pk_add_f32 v[120:121], v[120:121], 1.0 op_sel_hi:[1,0]
	v_pk_add_f32 v[122:123], v[122:123], 1.0 op_sel_hi:[1,0]
	v_pk_mul_f32 v[24:25], v[24:25], v[178:179] op_sel_hi:[1,0]
	v_pk_mul_f32 v[26:27], v[26:27], v[178:179] op_sel_hi:[1,0]
	v_pk_mul_f32 v[24:25], v[104:105], v[24:25]
	v_pk_mul_f32 v[26:27], v[106:107], v[26:27]
	v_pk_fma_f32 v[24:25], v[120:121], v[24:25], v[136:137]
	v_pk_fma_f32 v[26:27], v[122:123], v[26:27], v[138:139]
	v_cvt_pk_bf16_f32 v24, v24, v25
	v_cvt_pk_bf16_f32 v25, v26, v27
	global_store_dwordx2 v[182:183], v[24:25], off offset:512
	v_pk_mul_f32 v[8:9], v[8:9], v[180:181] op_sel_hi:[1,0]
	v_pk_mul_f32 v[10:11], v[10:11], v[180:181] op_sel_hi:[1,0]
	v_pk_mul_f32 v[8:9], v[104:105], v[8:9]
	v_pk_mul_f32 v[10:11], v[106:107], v[10:11]
	v_pk_fma_f32 v[8:9], v[120:121], v[8:9], v[136:137]
	v_pk_fma_f32 v[10:11], v[122:123], v[10:11], v[138:139]
	v_cvt_pk_bf16_f32 v8, v8, v9
	v_cvt_pk_bf16_f32 v9, v10, v11
	global_store_dwordx2 v[98:99], v[8:9], off offset:512
	v_pk_add_f32 v[124:125], v[124:125], 1.0 op_sel_hi:[1,0]
	v_pk_add_f32 v[126:127], v[126:127], 1.0 op_sel_hi:[1,0]
	v_pk_mul_f32 v[20:21], v[20:21], v[178:179] op_sel_hi:[1,0]
	v_pk_mul_f32 v[22:23], v[22:23], v[178:179] op_sel_hi:[1,0]
	v_pk_mul_f32 v[20:21], v[108:109], v[20:21]
	v_pk_mul_f32 v[22:23], v[110:111], v[22:23]
	v_pk_fma_f32 v[20:21], v[124:125], v[20:21], v[140:141]
	v_pk_fma_f32 v[22:23], v[126:127], v[22:23], v[142:143]
	v_cvt_pk_bf16_f32 v20, v20, v21
	v_cvt_pk_bf16_f32 v21, v22, v23
	global_store_dwordx2 v[182:183], v[20:21], off offset:1024
	v_pk_mul_f32 v[4:5], v[4:5], v[180:181] op_sel_hi:[1,0]
	v_pk_mul_f32 v[6:7], v[6:7], v[180:181] op_sel_hi:[1,0]
	v_pk_mul_f32 v[4:5], v[108:109], v[4:5]
	v_pk_mul_f32 v[6:7], v[110:111], v[6:7]
	v_pk_fma_f32 v[4:5], v[124:125], v[4:5], v[140:141]
	v_pk_fma_f32 v[6:7], v[126:127], v[6:7], v[142:143]
	v_cvt_pk_bf16_f32 v4, v4, v5
	v_cvt_pk_bf16_f32 v5, v6, v7
	global_store_dwordx2 v[98:99], v[4:5], off offset:1024
	v_pk_add_f32 v[128:129], v[128:129], 1.0 op_sel_hi:[1,0]
	v_pk_add_f32 v[130:131], v[130:131], 1.0 op_sel_hi:[1,0]
	v_pk_mul_f32 v[12:13], v[12:13], v[178:179] op_sel_hi:[1,0]
	v_pk_mul_f32 v[14:15], v[14:15], v[178:179] op_sel_hi:[1,0]
	v_pk_mul_f32 v[12:13], v[112:113], v[12:13]
	v_pk_mul_f32 v[14:15], v[114:115], v[14:15]
	v_pk_fma_f32 v[12:13], v[128:129], v[12:13], v[164:165]
	v_pk_fma_f32 v[14:15], v[130:131], v[14:15], v[166:167]
	v_cvt_pk_bf16_f32 v12, v12, v13
	v_cvt_pk_bf16_f32 v13, v14, v15
	global_store_dwordx2 v[182:183], v[12:13], off offset:1536
	v_pk_mul_f32 v[0:1], v[0:1], v[180:181] op_sel_hi:[1,0]
	v_pk_mul_f32 v[2:3], v[2:3], v[180:181] op_sel_hi:[1,0]
	v_pk_mul_f32 v[0:1], v[112:113], v[0:1]
	v_pk_mul_f32 v[2:3], v[114:115], v[2:3]
	v_pk_fma_f32 v[0:1], v[128:129], v[0:1], v[164:165]
	v_pk_fma_f32 v[2:3], v[130:131], v[2:3], v[166:167]
	v_cvt_pk_bf16_f32 v0, v0, v1
	v_cvt_pk_bf16_f32 v1, v2, v3
	global_store_dwordx2 v[98:99], v[0:1], off offset:1536
	s_waitcnt vmcnt(8)
	v_mov_b32_e32 v28, v184
	v_mov_b32_e32 v29, v185
	v_mov_b32_e32 v30, v186
	v_mov_b32_e32 v31, v187
	v_mov_b32_e32 v24, v188
	v_mov_b32_e32 v25, v189
	v_mov_b32_e32 v26, v190
	v_mov_b32_e32 v27, v191
	v_mov_b32_e32 v20, v200
	v_mov_b32_e32 v21, v201
	v_mov_b32_e32 v22, v202
	v_mov_b32_e32 v23, v203
	v_mov_b32_e32 v12, v204
	v_mov_b32_e32 v13, v205
	v_mov_b32_e32 v14, v206
	v_mov_b32_e32 v15, v207
	v_mov_b32_e32 v16, v208
	v_mov_b32_e32 v17, v209
	v_mov_b32_e32 v18, v210
	v_mov_b32_e32 v19, v211
	v_mov_b32_e32 v8, v240
	v_mov_b32_e32 v9, v241
	v_mov_b32_e32 v10, v242
	v_mov_b32_e32 v11, v243
	v_mov_b32_e32 v4, v244
	v_mov_b32_e32 v5, v245
	v_mov_b32_e32 v6, v246
	v_mov_b32_e32 v7, v247
	v_mov_b32_e32 v0, v248
	v_mov_b32_e32 v1, v249
	v_mov_b32_e32 v2, v250
	v_mov_b32_e32 v3, v251
	v_mov_b32_e32 v38, v232
	v_ashrrev_i32_e32 v39, 31, v232
	v_add_u32_e32 v46, 4, v232
	s_cmp_lg_u32 s45, 0
	v_ashrrev_i32_e32 v47, 31, v46
	s_cbranch_scc1 .Lnorm_loop2
	s_branch .LBB0_645
